# up GEMM loop: leading wave group defers its LDS-DMA vmcnt wait from before the pre-MFMA barrier to before the post-MFMA barrier
# baseline (speedup 1.0000x reference)
.LBB0_733:
	s_and_b64 vcc, exec, s[14:15]
	s_add_u32 s30, s26, 0xfffc0080
	s_addc_u32 s31, s27, -1
	s_add_i32 s87, 0, 0x10000
	s_cmp_eq_u32 s86, 12
	s_cselect_b32 s69, s19, s31
	s_cselect_b32 s68, s35, s30
	s_cselect_b32 s67, s17, s85
	s_cselect_b32 s66, s83, s84
	s_add_i32 s88, 0, 0x14000
	v_add_u32_e32 v156, s87, v146
	v_add_u32_e32 v172, s88, v146
	ds_read_b128 v[140:143], v156
	ds_read_b128 v[148:151], v156 offset:1024
	ds_read_b128 v[152:155], v156 offset:2048
	ds_read_b128 v[156:159], v156 offset:3072
	ds_read_b128 v[160:163], v172
	ds_read_b128 v[164:167], v172 offset:1024
	ds_read_b128 v[168:171], v172 offset:2048
	ds_read_b128 v[172:175], v172 offset:3072
	v_lshl_add_u64 v[208:209], s[26:27], 0, v[136:137]
	s_add_i32 m0, s75, 0xc000
	ds_read_b128 v[176:179], v147
	ds_read_b128 v[180:183], v147 offset:1024
	ds_read_b128 v[184:187], v147 offset:2048
	ds_read_b128 v[188:191], v147 offset:3072
	ds_read_b128 v[192:195], v147 offset:4096
	ds_read_b128 v[196:199], v147 offset:5120
	ds_read_b128 v[200:203], v147 offset:6144
	ds_read_b128 v[204:207], v147 offset:7168
	global_load_lds_dwordx4 v[208:209], off
	v_lshl_add_u64 v[208:209], s[26:27], 0, v[138:139]
	s_add_i32 m0, s75, 0xe000
	s_nop 0
	global_load_lds_dwordx4 v[208:209], off
	s_cbranch_vccnz .Ldw_up_1
	s_waitcnt vmcnt(8)
.Ldw_up_1:
	s_waitcnt lgkmcnt(0)
	s_barrier
	s_setprio 1
	s_waitcnt lgkmcnt(0)
	v_mfma_f32_16x16x32_bf16 v[126:129], v[140:143], v[176:179], v[126:129]
	v_mfma_f32_16x16x32_bf16 v[122:125], v[152:155], v[176:179], v[122:125]
	v_mfma_f32_16x16x32_bf16 v[110:113], v[140:143], v[184:187], v[110:113]
	v_mfma_f32_16x16x32_bf16 v[106:109], v[152:155], v[184:187], v[106:109]
	v_mfma_f32_16x16x32_bf16 v[92:95], v[140:143], v[192:195], v[92:95]
	v_mfma_f32_16x16x32_bf16 v[88:91], v[152:155], v[192:195], v[88:91]
	v_mfma_f32_16x16x32_bf16 v[76:79], v[140:143], v[200:203], v[76:79]
	v_mfma_f32_16x16x32_bf16 v[72:75], v[152:155], v[200:203], v[72:75]
	v_mfma_f32_16x16x32_bf16 v[126:129], v[148:151], v[180:183], v[126:129]
	v_mfma_f32_16x16x32_bf16 v[122:125], v[156:159], v[180:183], v[122:125]
	v_mfma_f32_16x16x32_bf16 v[110:113], v[148:151], v[188:191], v[110:113]
	v_mfma_f32_16x16x32_bf16 v[106:109], v[156:159], v[188:191], v[106:109]
	v_mfma_f32_16x16x32_bf16 v[92:95], v[148:151], v[196:199], v[92:95]
	v_mfma_f32_16x16x32_bf16 v[88:91], v[156:159], v[196:199], v[88:91]
	v_mfma_f32_16x16x32_bf16 v[76:79], v[148:151], v[204:207], v[76:79]
	v_mfma_f32_16x16x32_bf16 v[72:75], v[156:159], v[204:207], v[72:75]
	s_setprio 0
	s_setprio 1
	v_mfma_f32_16x16x32_bf16 v[118:121], v[160:163], v[176:179], v[118:121]
	v_mfma_f32_16x16x32_bf16 v[114:117], v[168:171], v[176:179], v[114:117]
	v_mfma_f32_16x16x32_bf16 v[102:105], v[160:163], v[184:187], v[102:105]
	v_mfma_f32_16x16x32_bf16 v[98:101], v[168:171], v[184:187], v[98:101]
	v_mfma_f32_16x16x32_bf16 v[84:87], v[160:163], v[192:195], v[84:87]
	v_mfma_f32_16x16x32_bf16 v[80:83], v[168:171], v[192:195], v[80:83]
	v_mfma_f32_16x16x32_bf16 v[68:71], v[160:163], v[200:203], v[68:71]
	v_mfma_f32_16x16x32_bf16 v[64:67], v[168:171], v[200:203], v[64:67]
	v_mfma_f32_16x16x32_bf16 v[118:121], v[164:167], v[180:183], v[118:121]
	v_mfma_f32_16x16x32_bf16 v[114:117], v[172:175], v[180:183], v[114:117]
	v_mfma_f32_16x16x32_bf16 v[102:105], v[164:167], v[188:191], v[102:105]
	v_mfma_f32_16x16x32_bf16 v[98:101], v[172:175], v[188:191], v[98:101]
	v_mfma_f32_16x16x32_bf16 v[84:87], v[164:167], v[196:199], v[84:87]
	v_mfma_f32_16x16x32_bf16 v[80:83], v[172:175], v[196:199], v[80:83]
	v_mfma_f32_16x16x32_bf16 v[68:71], v[164:167], v[204:207], v[68:71]
	v_mfma_f32_16x16x32_bf16 v[64:67], v[172:175], v[204:207], v[64:67]
	s_setprio 0
	s_waitcnt vmcnt(8)
	s_barrier
	s_add_i32 s30, s87, s63
	v_lshl_add_u64 v[208:209], s[66:67], 0, v[96:97]
	s_mov_b32 m0, s30
	ds_read_b128 v[176:179], v147 offset:16384
	ds_read_b128 v[180:183], v147 offset:17408
	ds_read_b128 v[184:187], v147 offset:18432
	ds_read_b128 v[188:191], v147 offset:19456
	ds_read_b128 v[192:195], v147 offset:20480
	ds_read_b128 v[196:199], v147 offset:21504
	ds_read_b128 v[200:203], v147 offset:22528
	ds_read_b128 v[204:207], v147 offset:23552
	global_load_lds_dwordx4 v[208:209], off
	s_add_i32 m0, s30, 0x2000
	s_add_u32 s30, s66, 0x40000
	v_lshl_add_u64 v[210:211], s[66:67], 0, v[130:131]
	s_addc_u32 s31, s67, 0
	s_add_i32 s87, s88, s63
	global_load_lds_dwordx4 v[210:211], off
	v_lshl_add_u64 v[216:217], s[30:31], 0, v[96:97]
	s_mov_b32 m0, s87
	v_lshl_add_u64 v[218:219], s[68:69], 0, v[132:133]
	global_load_lds_dwordx4 v[216:217], off
	v_lshl_add_u64 v[216:217], s[30:31], 0, v[130:131]
	s_add_i32 m0, s87, 0x2000
	s_nop 0
	global_load_lds_dwordx4 v[216:217], off
	v_lshl_add_u64 v[216:217], s[68:69], 0, v[134:135]
	s_mov_b32 m0, s75
	s_nop 0
	global_load_lds_dwordx4 v[216:217], off
	s_mov_b32 m0, s76
	s_nop 0
	global_load_lds_dwordx4 v[218:219], off
	s_cbranch_vccnz .Ldw_up_2
	s_waitcnt vmcnt(8)
.Ldw_up_2:
	s_waitcnt lgkmcnt(0)
	s_barrier
	s_setprio 1
	s_waitcnt lgkmcnt(0)
	v_mfma_f32_16x16x32_bf16 v[60:63], v[140:143], v[176:179], v[60:63]
	v_mfma_f32_16x16x32_bf16 v[56:59], v[152:155], v[176:179], v[56:59]
	v_mfma_f32_16x16x32_bf16 v[44:47], v[140:143], v[184:187], v[44:47]
	v_mfma_f32_16x16x32_bf16 v[40:43], v[152:155], v[184:187], v[40:43]
	v_mfma_f32_16x16x32_bf16 v[28:31], v[140:143], v[192:195], v[28:31]
	v_mfma_f32_16x16x32_bf16 v[24:27], v[152:155], v[192:195], v[24:27]
	v_mfma_f32_16x16x32_bf16 v[12:15], v[140:143], v[200:203], v[12:15]
	v_mfma_f32_16x16x32_bf16 v[8:11], v[152:155], v[200:203], v[8:11]
	v_mfma_f32_16x16x32_bf16 v[60:63], v[148:151], v[180:183], v[60:63]
	v_mfma_f32_16x16x32_bf16 v[56:59], v[156:159], v[180:183], v[56:59]
	v_mfma_f32_16x16x32_bf16 v[44:47], v[148:151], v[188:191], v[44:47]
	v_mfma_f32_16x16x32_bf16 v[40:43], v[156:159], v[188:191], v[40:43]
	v_mfma_f32_16x16x32_bf16 v[28:31], v[148:151], v[196:199], v[28:31]
	v_mfma_f32_16x16x32_bf16 v[24:27], v[156:159], v[196:199], v[24:27]
	v_mfma_f32_16x16x32_bf16 v[12:15], v[148:151], v[204:207], v[12:15]
	v_mfma_f32_16x16x32_bf16 v[8:11], v[156:159], v[204:207], v[8:11]
	s_setprio 0
	s_setprio 1
	v_mfma_f32_16x16x32_bf16 v[52:55], v[160:163], v[176:179], v[52:55]
	v_mfma_f32_16x16x32_bf16 v[48:51], v[168:171], v[176:179], v[48:51]
	v_mfma_f32_16x16x32_bf16 v[36:39], v[160:163], v[184:187], v[36:39]
	v_mfma_f32_16x16x32_bf16 v[32:35], v[168:171], v[184:187], v[32:35]
	v_mfma_f32_16x16x32_bf16 v[20:23], v[160:163], v[192:195], v[20:23]
	v_mfma_f32_16x16x32_bf16 v[16:19], v[168:171], v[192:195], v[16:19]
	v_mfma_f32_16x16x32_bf16 v[4:7], v[160:163], v[200:203], v[4:7]
	v_mfma_f32_16x16x32_bf16 v[0:3], v[168:171], v[200:203], v[0:3]
	v_mfma_f32_16x16x32_bf16 v[52:55], v[164:167], v[180:183], v[52:55]
	v_mfma_f32_16x16x32_bf16 v[48:51], v[172:175], v[180:183], v[48:51]
	v_mfma_f32_16x16x32_bf16 v[36:39], v[164:167], v[188:191], v[36:39]
	v_mfma_f32_16x16x32_bf16 v[32:35], v[172:175], v[188:191], v[32:35]
	v_mfma_f32_16x16x32_bf16 v[20:23], v[164:167], v[196:199], v[20:23]
	v_mfma_f32_16x16x32_bf16 v[16:19], v[172:175], v[196:199], v[16:19]
	v_mfma_f32_16x16x32_bf16 v[4:7], v[164:167], v[204:207], v[4:7]
	v_mfma_f32_16x16x32_bf16 v[0:3], v[172:175], v[204:207], v[0:3]
	s_setprio 0
	s_waitcnt vmcnt(8)
	s_barrier
	s_add_i32 s87, 0, 0x18000
	s_add_i32 s88, 0, 0x1c000
	v_add_u32_e32 v156, s87, v146
	v_add_u32_e32 v172, s88, v146
	ds_read_b128 v[140:143], v156
	ds_read_b128 v[148:151], v156 offset:1024
	ds_read_b128 v[152:155], v156 offset:2048
	ds_read_b128 v[156:159], v156 offset:3072
	ds_read_b128 v[160:163], v172
	ds_read_b128 v[164:167], v172 offset:1024
	ds_read_b128 v[168:171], v172 offset:2048
	ds_read_b128 v[172:175], v172 offset:3072
	s_add_u32 s30, s68, 0x40000
	s_addc_u32 s31, s69, 0
	s_mov_b32 m0, s77
	v_lshl_add_u64 v[220:221], s[30:31], 0, v[134:135]
	ds_read_b128 v[176:179], v147 offset:32768
	ds_read_b128 v[180:183], v147 offset:33792
	ds_read_b128 v[184:187], v147 offset:34816
	ds_read_b128 v[188:191], v147 offset:35840
	ds_read_b128 v[192:195], v147 offset:36864
	ds_read_b128 v[196:199], v147 offset:37888
	ds_read_b128 v[200:203], v147 offset:38912
	ds_read_b128 v[204:207], v147 offset:39936
	global_load_lds_dwordx4 v[220:221], off
	v_lshl_add_u64 v[220:221], s[30:31], 0, v[132:133]
	s_mov_b32 m0, s78
	s_nop 0
	global_load_lds_dwordx4 v[220:221], off
	s_cbranch_vccnz .Ldw_up_3
	s_waitcnt vmcnt(8)
.Ldw_up_3:
	s_waitcnt lgkmcnt(0)
	s_barrier
	s_setprio 1
	s_waitcnt lgkmcnt(0)
	v_mfma_f32_16x16x32_bf16 v[126:129], v[140:143], v[176:179], v[126:129]
	v_mfma_f32_16x16x32_bf16 v[122:125], v[152:155], v[176:179], v[122:125]
	v_mfma_f32_16x16x32_bf16 v[110:113], v[140:143], v[184:187], v[110:113]
	v_mfma_f32_16x16x32_bf16 v[106:109], v[152:155], v[184:187], v[106:109]
	v_mfma_f32_16x16x32_bf16 v[92:95], v[140:143], v[192:195], v[92:95]
	v_mfma_f32_16x16x32_bf16 v[88:91], v[152:155], v[192:195], v[88:91]
	v_mfma_f32_16x16x32_bf16 v[76:79], v[140:143], v[200:203], v[76:79]
	v_mfma_f32_16x16x32_bf16 v[72:75], v[152:155], v[200:203], v[72:75]
	v_mfma_f32_16x16x32_bf16 v[126:129], v[148:151], v[180:183], v[126:129]
	v_mfma_f32_16x16x32_bf16 v[122:125], v[156:159], v[180:183], v[122:125]
	v_mfma_f32_16x16x32_bf16 v[110:113], v[148:151], v[188:191], v[110:113]
	v_mfma_f32_16x16x32_bf16 v[106:109], v[156:159], v[188:191], v[106:109]
	v_mfma_f32_16x16x32_bf16 v[92:95], v[148:151], v[196:199], v[92:95]
	v_mfma_f32_16x16x32_bf16 v[88:91], v[156:159], v[196:199], v[88:91]
	v_mfma_f32_16x16x32_bf16 v[76:79], v[148:151], v[204:207], v[76:79]
	v_mfma_f32_16x16x32_bf16 v[72:75], v[156:159], v[204:207], v[72:75]
	s_setprio 0
	s_setprio 1
	v_mfma_f32_16x16x32_bf16 v[118:121], v[160:163], v[176:179], v[118:121]
	v_mfma_f32_16x16x32_bf16 v[114:117], v[168:171], v[176:179], v[114:117]
	v_mfma_f32_16x16x32_bf16 v[102:105], v[160:163], v[184:187], v[102:105]
	v_mfma_f32_16x16x32_bf16 v[98:101], v[168:171], v[184:187], v[98:101]
	v_mfma_f32_16x16x32_bf16 v[84:87], v[160:163], v[192:195], v[84:87]
	v_mfma_f32_16x16x32_bf16 v[80:83], v[168:171], v[192:195], v[80:83]
	v_mfma_f32_16x16x32_bf16 v[68:71], v[160:163], v[200:203], v[68:71]
	v_mfma_f32_16x16x32_bf16 v[64:67], v[168:171], v[200:203], v[64:67]
	v_mfma_f32_16x16x32_bf16 v[118:121], v[164:167], v[180:183], v[118:121]
	v_mfma_f32_16x16x32_bf16 v[114:117], v[172:175], v[180:183], v[114:117]
	v_mfma_f32_16x16x32_bf16 v[102:105], v[164:167], v[188:191], v[102:105]
	v_mfma_f32_16x16x32_bf16 v[98:101], v[172:175], v[188:191], v[98:101]
	v_mfma_f32_16x16x32_bf16 v[84:87], v[164:167], v[196:199], v[84:87]
	v_mfma_f32_16x16x32_bf16 v[80:83], v[172:175], v[196:199], v[80:83]
	v_mfma_f32_16x16x32_bf16 v[68:71], v[164:167], v[204:207], v[68:71]
	v_mfma_f32_16x16x32_bf16 v[64:67], v[172:175], v[204:207], v[64:67]
	s_setprio 0
	s_waitcnt vmcnt(8)
	s_barrier
	s_add_i32 s30, s87, s63
	v_lshl_add_u64 v[208:209], v[208:209], 0, s[48:49]
	s_mov_b32 m0, s30
	ds_read_b128 v[176:179], v147 offset:49152
	ds_read_b128 v[180:183], v147 offset:50176
	ds_read_b128 v[184:187], v147 offset:51200
	ds_read_b128 v[188:191], v147 offset:52224
	ds_read_b128 v[192:195], v147 offset:53248
	ds_read_b128 v[196:199], v147 offset:54272
	ds_read_b128 v[200:203], v147 offset:55296
	ds_read_b128 v[204:207], v147 offset:56320
	global_load_lds_dwordx4 v[208:209], off
	s_add_i32 m0, s30, 0x2000
	s_add_u32 s30, s66, 0x40080
	v_lshl_add_u64 v[208:209], v[210:211], 0, s[48:49]
	s_addc_u32 s31, s67, 0
	s_add_i32 s66, s88, s63
	global_load_lds_dwordx4 v[208:209], off
	v_lshl_add_u64 v[208:209], s[30:31], 0, v[96:97]
	s_mov_b32 m0, s66
	s_nop 0
	global_load_lds_dwordx4 v[208:209], off
	v_lshl_add_u64 v[208:209], s[30:31], 0, v[130:131]
	s_add_i32 m0, s66, 0x2000
	s_nop 0
	global_load_lds_dwordx4 v[208:209], off
	v_lshl_add_u64 v[208:209], v[216:217], 0, s[48:49]
	s_mov_b32 m0, s80
	s_nop 0
	global_load_lds_dwordx4 v[208:209], off
	v_lshl_add_u64 v[208:209], v[218:219], 0, s[48:49]
	s_mov_b32 m0, s81
	s_nop 0
	global_load_lds_dwordx4 v[208:209], off
	s_cbranch_vccnz .Ldw_up_4
	s_waitcnt vmcnt(8)
.Ldw_up_4:
	s_waitcnt lgkmcnt(0)
	s_barrier
	s_setprio 1
	s_waitcnt lgkmcnt(0)
	v_mfma_f32_16x16x32_bf16 v[60:63], v[140:143], v[176:179], v[60:63]
	v_mfma_f32_16x16x32_bf16 v[56:59], v[152:155], v[176:179], v[56:59]
	v_mfma_f32_16x16x32_bf16 v[44:47], v[140:143], v[184:187], v[44:47]
	v_mfma_f32_16x16x32_bf16 v[40:43], v[152:155], v[184:187], v[40:43]
	v_mfma_f32_16x16x32_bf16 v[28:31], v[140:143], v[192:195], v[28:31]
	v_mfma_f32_16x16x32_bf16 v[24:27], v[152:155], v[192:195], v[24:27]
	v_mfma_f32_16x16x32_bf16 v[12:15], v[140:143], v[200:203], v[12:15]
	v_mfma_f32_16x16x32_bf16 v[8:11], v[152:155], v[200:203], v[8:11]
	v_mfma_f32_16x16x32_bf16 v[60:63], v[148:151], v[180:183], v[60:63]
	v_mfma_f32_16x16x32_bf16 v[56:59], v[156:159], v[180:183], v[56:59]
	v_mfma_f32_16x16x32_bf16 v[44:47], v[148:151], v[188:191], v[44:47]
	v_mfma_f32_16x16x32_bf16 v[40:43], v[156:159], v[188:191], v[40:43]
	v_mfma_f32_16x16x32_bf16 v[28:31], v[148:151], v[196:199], v[28:31]
	v_mfma_f32_16x16x32_bf16 v[24:27], v[156:159], v[196:199], v[24:27]
	v_mfma_f32_16x16x32_bf16 v[12:15], v[148:151], v[204:207], v[12:15]
	v_mfma_f32_16x16x32_bf16 v[8:11], v[156:159], v[204:207], v[8:11]
	s_setprio 0
	s_setprio 1
	v_mfma_f32_16x16x32_bf16 v[52:55], v[160:163], v[176:179], v[52:55]
	v_mfma_f32_16x16x32_bf16 v[48:51], v[168:171], v[176:179], v[48:51]
	v_mfma_f32_16x16x32_bf16 v[36:39], v[160:163], v[184:187], v[36:39]
	v_mfma_f32_16x16x32_bf16 v[32:35], v[168:171], v[184:187], v[32:35]
	v_mfma_f32_16x16x32_bf16 v[20:23], v[160:163], v[192:195], v[20:23]
	v_mfma_f32_16x16x32_bf16 v[16:19], v[168:171], v[192:195], v[16:19]
	v_mfma_f32_16x16x32_bf16 v[4:7], v[160:163], v[200:203], v[4:7]
	v_mfma_f32_16x16x32_bf16 v[0:3], v[168:171], v[200:203], v[0:3]
	v_mfma_f32_16x16x32_bf16 v[52:55], v[164:167], v[180:183], v[52:55]
	v_mfma_f32_16x16x32_bf16 v[48:51], v[172:175], v[180:183], v[48:51]
	v_mfma_f32_16x16x32_bf16 v[36:39], v[164:167], v[188:191], v[36:39]
	v_mfma_f32_16x16x32_bf16 v[32:35], v[172:175], v[188:191], v[32:35]
	v_mfma_f32_16x16x32_bf16 v[20:23], v[164:167], v[196:199], v[20:23]
	v_mfma_f32_16x16x32_bf16 v[16:19], v[172:175], v[196:199], v[16:19]
	v_mfma_f32_16x16x32_bf16 v[4:7], v[164:167], v[204:207], v[4:7]
	v_mfma_f32_16x16x32_bf16 v[0:3], v[172:175], v[204:207], v[0:3]
	s_setprio 0
	s_waitcnt vmcnt(8)
	s_barrier
	s_add_i32 s86, s86, 2
	s_add_u32 s26, s26, 0x100
	s_addc_u32 s27, s27, 0
	s_add_u32 s84, s84, 0x100
	s_addc_u32 s85, s85, 0
	s_cmp_gt_u32 s86, 13
	s_cbranch_scc0 .LBB0_733
	s_and_b64 vcc, exec, s[14:15]
	s_cbranch_vccz .LBB0_736
	s_barrier
